# attention fast loop: each tile's 4 K/V LDS-DMA pieces issued one by one inside the next sub-tile's VALU-only exp stretches instead of a burst behind the rendezvous barrier
# speedup vs baseline: 1.0012x; 1.0012x over previous
.Lat_fbacka:
	v_exp_f32_e32 v96, v96
	v_exp_f32_e32 v97, v97
	v_exp_f32_e32 v98, v98
	v_exp_f32_e32 v99, v99
	s_cmp_eq_u32 s33, 0
	s_cbranch_scc1 .Lat_dvF00
	s_add_u32 m0, s51, 0x8000
	s_nop 0
	global_load_lds_dwordx4 v158, s[36:37]
.Lat_dvF00:
	v_exp_f32_e32 v100, v100
	v_exp_f32_e32 v101, v101
	v_exp_f32_e32 v102, v102
	v_exp_f32_e32 v103, v103
	s_cmp_eq_u32 s33, 0
	s_cbranch_scc1 .Lat_dvF01
	s_add_u32 m0, s51, 0xa000
	s_nop 0
	global_load_lds_dwordx4 v159, s[36:37]
	s_add_u32 s36, s36, 0x4000
	s_addc_u32 s37, s37, 0
.Lat_dvF01:
	v_cvt_pk_bf16_f32 v162, v96, v97
	v_cvt_pk_bf16_f32 v163, v98, v99
	v_cvt_pk_bf16_f32 v164, v100, v101
	v_cvt_pk_bf16_f32 v165, v102, v103
	v_pk_add_f32 v[128:129], v[128:129], v[96:97]
	v_pk_add_f32 v[128:129], v[128:129], v[98:99]
	v_pk_add_f32 v[128:129], v[128:129], v[100:101]
	v_pk_add_f32 v[128:129], v[128:129], v[102:103]
	s_waitcnt lgkmcnt(12)
	v_mfma_f32_32x32x16_bf16 v[0:15], v[162:165], v[168:171], v[0:15]
	v_exp_f32_e32 v104, v104
	v_exp_f32_e32 v105, v105
	v_exp_f32_e32 v106, v106
	v_exp_f32_e32 v107, v107
	v_mfma_f32_32x32x16_bf16 v[16:31], v[162:165], v[172:175], v[16:31]
	v_exp_f32_e32 v108, v108
	v_exp_f32_e32 v109, v109
	v_exp_f32_e32 v110, v110
	v_exp_f32_e32 v111, v111
	v_cvt_pk_bf16_f32 v162, v104, v105
	v_cvt_pk_bf16_f32 v163, v106, v107
	v_cvt_pk_bf16_f32 v164, v108, v109
	v_cvt_pk_bf16_f32 v165, v110, v111
	v_pk_add_f32 v[128:129], v[128:129], v[104:105]
	v_pk_add_f32 v[128:129], v[128:129], v[106:107]
	v_pk_add_f32 v[128:129], v[128:129], v[108:109]
	v_pk_add_f32 v[128:129], v[128:129], v[110:111]
	s_waitcnt lgkmcnt(8)
	v_mfma_f32_32x32x16_bf16 v[0:15], v[162:165], v[176:179], v[0:15]
	v_exp_f32_e32 v112, v112
	v_exp_f32_e32 v113, v113
	v_exp_f32_e32 v114, v114
	v_exp_f32_e32 v115, v115
	v_mfma_f32_32x32x16_bf16 v[16:31], v[162:165], v[180:183], v[16:31]
	v_mfma_f32_32x32x16_bf16 v[96:111], v[48:51], v[150:153], v[64:79]
	v_exp_f32_e32 v116, v116
	v_exp_f32_e32 v117, v117
	v_exp_f32_e32 v118, v118
	v_exp_f32_e32 v119, v119
	v_mfma_f32_32x32x16_bf16 v[96:111], v[52:55], v[154:157], v[96:111]
	v_cvt_pk_bf16_f32 v162, v112, v113
	v_cvt_pk_bf16_f32 v163, v114, v115
	v_cvt_pk_bf16_f32 v164, v116, v117
	v_cvt_pk_bf16_f32 v165, v118, v119
	v_pk_add_f32 v[128:129], v[128:129], v[112:113]
	v_pk_add_f32 v[128:129], v[128:129], v[114:115]
	v_pk_add_f32 v[128:129], v[128:129], v[116:117]
	v_pk_add_f32 v[128:129], v[128:129], v[118:119]
	s_waitcnt lgkmcnt(4)
	v_mfma_f32_32x32x16_bf16 v[0:15], v[162:165], v[184:187], v[0:15]
	v_exp_f32_e32 v120, v120
	v_exp_f32_e32 v121, v121
	v_exp_f32_e32 v122, v122
	v_exp_f32_e32 v123, v123
	v_mfma_f32_32x32x16_bf16 v[16:31], v[162:165], v[188:191], v[16:31]
	v_exp_f32_e32 v124, v124
	v_exp_f32_e32 v125, v125
	v_exp_f32_e32 v126, v126
	v_exp_f32_e32 v127, v127
	v_cvt_pk_bf16_f32 v162, v120, v121
	v_cvt_pk_bf16_f32 v163, v122, v123
	v_cvt_pk_bf16_f32 v164, v124, v125
	v_cvt_pk_bf16_f32 v165, v126, v127
	v_pk_add_f32 v[128:129], v[128:129], v[120:121]
	v_pk_add_f32 v[128:129], v[128:129], v[122:123]
	v_pk_add_f32 v[128:129], v[128:129], v[124:125]
	v_pk_add_f32 v[128:129], v[128:129], v[126:127]
	v_mfma_f32_32x32x16_bf16 v[112:127], v[56:59], v[150:153], v[64:79]
	v_mfma_f32_32x32x16_bf16 v[112:127], v[60:63], v[154:157], v[112:127]
	s_waitcnt lgkmcnt(0)
	v_mfma_f32_32x32x16_bf16 v[0:15], v[162:165], v[192:195], v[0:15]
	v_mfma_f32_32x32x16_bf16 v[16:31], v[162:165], v[196:199], v[16:31]
	ds_read_b128 v[48:51], v144 offset:8192
	ds_read_b128 v[52:55], v145 offset:8192
	ds_read_b128 v[56:59], v144 offset:12288
	ds_read_b128 v[60:63], v145 offset:12288
	s_cmp_lg_u32 s95, 0
	s_cbranch_scc1 .Lat_ffirstb
.Lat_fbackb:
	v_exp_f32_e32 v96, v96
	v_exp_f32_e32 v97, v97
	v_exp_f32_e32 v98, v98
	v_exp_f32_e32 v99, v99
	s_cmp_eq_u32 s33, 0
	s_cbranch_scc1 .Lat_dvF02
	s_add_u32 m0, s51, 0x14000
	s_nop 0
	global_load_lds_dwordx4 v160, s[48:49]
.Lat_dvF02:
	v_exp_f32_e32 v100, v100
	v_exp_f32_e32 v101, v101
	v_exp_f32_e32 v102, v102
	v_exp_f32_e32 v103, v103
	s_cmp_eq_u32 s33, 0
	s_cbranch_scc1 .Lat_dvF03
	s_add_u32 m0, s51, 0x16000
	s_nop 0
	global_load_lds_dwordx4 v161, s[48:49]
	s_add_u32 s48, s48, 0x4000
	s_addc_u32 s49, s49, 0
.Lat_dvF03:
	v_cvt_pk_bf16_f32 v162, v96, v97
	v_cvt_pk_bf16_f32 v163, v98, v99
	v_cvt_pk_bf16_f32 v164, v100, v101
	v_cvt_pk_bf16_f32 v165, v102, v103
	v_pk_add_f32 v[130:131], v[130:131], v[96:97]
	v_pk_add_f32 v[130:131], v[130:131], v[98:99]
	v_pk_add_f32 v[130:131], v[130:131], v[100:101]
	v_pk_add_f32 v[130:131], v[130:131], v[102:103]
	v_mfma_f32_32x32x16_bf16 v[80:95], v[162:165], v[168:171], v[80:95]
	v_exp_f32_e32 v104, v104
	v_exp_f32_e32 v105, v105
	v_exp_f32_e32 v106, v106
	v_exp_f32_e32 v107, v107
	v_mfma_f32_32x32x16_bf16 v[200:215], v[162:165], v[172:175], v[200:215]
	v_exp_f32_e32 v108, v108
	v_exp_f32_e32 v109, v109
	v_exp_f32_e32 v110, v110
	v_exp_f32_e32 v111, v111
	v_cvt_pk_bf16_f32 v162, v104, v105
	v_cvt_pk_bf16_f32 v163, v106, v107
	v_cvt_pk_bf16_f32 v164, v108, v109
	v_cvt_pk_bf16_f32 v165, v110, v111
	v_pk_add_f32 v[130:131], v[130:131], v[104:105]
	v_pk_add_f32 v[130:131], v[130:131], v[106:107]
	v_pk_add_f32 v[130:131], v[130:131], v[108:109]
	v_pk_add_f32 v[130:131], v[130:131], v[110:111]
	v_mfma_f32_32x32x16_bf16 v[80:95], v[162:165], v[176:179], v[80:95]
	v_exp_f32_e32 v112, v112
	v_exp_f32_e32 v113, v113
	v_exp_f32_e32 v114, v114
	v_exp_f32_e32 v115, v115
	v_mfma_f32_32x32x16_bf16 v[200:215], v[162:165], v[180:183], v[200:215]
	v_exp_f32_e32 v116, v116
	v_exp_f32_e32 v117, v117
	v_exp_f32_e32 v118, v118
	v_exp_f32_e32 v119, v119
	v_cvt_pk_bf16_f32 v162, v112, v113
	v_cvt_pk_bf16_f32 v163, v114, v115
	v_cvt_pk_bf16_f32 v164, v116, v117
	v_cvt_pk_bf16_f32 v165, v118, v119
	v_pk_add_f32 v[130:131], v[130:131], v[112:113]
	v_pk_add_f32 v[130:131], v[130:131], v[114:115]
	v_pk_add_f32 v[130:131], v[130:131], v[116:117]
	v_pk_add_f32 v[130:131], v[130:131], v[118:119]
	v_mfma_f32_32x32x16_bf16 v[80:95], v[162:165], v[184:187], v[80:95]
	v_exp_f32_e32 v120, v120
	v_exp_f32_e32 v121, v121
	v_exp_f32_e32 v122, v122
	v_exp_f32_e32 v123, v123
	v_mfma_f32_32x32x16_bf16 v[200:215], v[162:165], v[188:191], v[200:215]
	v_exp_f32_e32 v124, v124
	v_exp_f32_e32 v125, v125
	v_exp_f32_e32 v126, v126
	v_exp_f32_e32 v127, v127
	v_cvt_pk_bf16_f32 v162, v120, v121
	v_cvt_pk_bf16_f32 v163, v122, v123
	v_cvt_pk_bf16_f32 v164, v124, v125
	v_cvt_pk_bf16_f32 v165, v126, v127
	v_pk_add_f32 v[130:131], v[130:131], v[120:121]
	v_pk_add_f32 v[130:131], v[130:131], v[122:123]
	v_pk_add_f32 v[130:131], v[130:131], v[124:125]
	v_pk_add_f32 v[130:131], v[130:131], v[126:127]
	v_mfma_f32_32x32x16_bf16 v[80:95], v[162:165], v[192:195], v[80:95]
	v_mfma_f32_32x32x16_bf16 v[200:215], v[162:165], v[196:199], v[200:215]
	s_waitcnt lgkmcnt(0)
	v_mfma_f32_32x32x16_bf16 v[96:111], v[48:51], v[136:139], v[32:47]
	ds_read_b64_tr_b16 v[168:169], v146 offset:8192
	ds_read_b64_tr_b16 v[170:171], v146 offset:9216
	ds_read_b64_tr_b16 v[172:173], v146 offset:8704
	ds_read_b64_tr_b16 v[174:175], v146 offset:9728
	v_mfma_f32_32x32x16_bf16 v[96:111], v[52:55], v[140:143], v[96:111]
	ds_read_b64_tr_b16 v[176:177], v146 offset:10240
	ds_read_b64_tr_b16 v[178:179], v146 offset:11264
	ds_read_b64_tr_b16 v[180:181], v146 offset:10752
	ds_read_b64_tr_b16 v[182:183], v146 offset:11776
	v_mfma_f32_32x32x16_bf16 v[112:127], v[56:59], v[136:139], v[32:47]
	ds_read_b64_tr_b16 v[184:185], v146 offset:12288
	ds_read_b64_tr_b16 v[186:187], v146 offset:13312
	ds_read_b64_tr_b16 v[188:189], v146 offset:12800
	ds_read_b64_tr_b16 v[190:191], v146 offset:13824
	v_mfma_f32_32x32x16_bf16 v[112:127], v[60:63], v[140:143], v[112:127]
	ds_read_b64_tr_b16 v[192:193], v146 offset:14336
	ds_read_b64_tr_b16 v[194:195], v146 offset:15360
	ds_read_b64_tr_b16 v[196:197], v146 offset:14848
	ds_read_b64_tr_b16 v[198:199], v146 offset:15872
	v_exp_f32_e32 v96, v96
	v_exp_f32_e32 v97, v97
	v_exp_f32_e32 v98, v98
	v_exp_f32_e32 v99, v99
	v_exp_f32_e32 v100, v100
	v_exp_f32_e32 v101, v101
	v_exp_f32_e32 v102, v102
	v_exp_f32_e32 v103, v103
	v_cvt_pk_bf16_f32 v162, v96, v97
	v_cvt_pk_bf16_f32 v163, v98, v99
	v_cvt_pk_bf16_f32 v164, v100, v101
	v_cvt_pk_bf16_f32 v165, v102, v103
	v_pk_add_f32 v[128:129], v[128:129], v[96:97]
	v_pk_add_f32 v[128:129], v[128:129], v[98:99]
	v_pk_add_f32 v[128:129], v[128:129], v[100:101]
	v_pk_add_f32 v[128:129], v[128:129], v[102:103]
	s_waitcnt lgkmcnt(12)
	v_mfma_f32_32x32x16_bf16 v[0:15], v[162:165], v[168:171], v[0:15]
	v_exp_f32_e32 v104, v104
	v_exp_f32_e32 v105, v105
	v_exp_f32_e32 v106, v106
	v_exp_f32_e32 v107, v107
	v_mfma_f32_32x32x16_bf16 v[16:31], v[162:165], v[172:175], v[16:31]
	v_exp_f32_e32 v108, v108
	v_exp_f32_e32 v109, v109
	v_exp_f32_e32 v110, v110
	v_exp_f32_e32 v111, v111
	v_cvt_pk_bf16_f32 v162, v104, v105
	v_cvt_pk_bf16_f32 v163, v106, v107
	v_cvt_pk_bf16_f32 v164, v108, v109
	v_cvt_pk_bf16_f32 v165, v110, v111
	v_pk_add_f32 v[128:129], v[128:129], v[104:105]
	v_pk_add_f32 v[128:129], v[128:129], v[106:107]
	v_pk_add_f32 v[128:129], v[128:129], v[108:109]
	v_pk_add_f32 v[128:129], v[128:129], v[110:111]
	s_waitcnt lgkmcnt(8)
	v_mfma_f32_32x32x16_bf16 v[0:15], v[162:165], v[176:179], v[0:15]
	v_exp_f32_e32 v112, v112
	v_exp_f32_e32 v113, v113
	v_exp_f32_e32 v114, v114
	v_exp_f32_e32 v115, v115
	v_mfma_f32_32x32x16_bf16 v[16:31], v[162:165], v[180:183], v[16:31]
	v_mfma_f32_32x32x16_bf16 v[96:111], v[48:51], v[150:153], v[64:79]
	v_exp_f32_e32 v116, v116
	v_exp_f32_e32 v117, v117
	v_exp_f32_e32 v118, v118
	v_exp_f32_e32 v119, v119
	v_mfma_f32_32x32x16_bf16 v[96:111], v[52:55], v[154:157], v[96:111]
	v_cvt_pk_bf16_f32 v162, v112, v113
	v_cvt_pk_bf16_f32 v163, v114, v115
	v_cvt_pk_bf16_f32 v164, v116, v117
	v_cvt_pk_bf16_f32 v165, v118, v119
	v_pk_add_f32 v[128:129], v[128:129], v[112:113]
	v_pk_add_f32 v[128:129], v[128:129], v[114:115]
	v_pk_add_f32 v[128:129], v[128:129], v[116:117]
	v_pk_add_f32 v[128:129], v[128:129], v[118:119]
	s_waitcnt lgkmcnt(4)
	v_mfma_f32_32x32x16_bf16 v[0:15], v[162:165], v[184:187], v[0:15]
	v_exp_f32_e32 v120, v120
	v_exp_f32_e32 v121, v121
	v_exp_f32_e32 v122, v122
	v_exp_f32_e32 v123, v123
	v_mfma_f32_32x32x16_bf16 v[16:31], v[162:165], v[188:191], v[16:31]
	v_exp_f32_e32 v124, v124
	v_exp_f32_e32 v125, v125
	v_exp_f32_e32 v126, v126
	v_exp_f32_e32 v127, v127
	v_cvt_pk_bf16_f32 v162, v120, v121
	v_cvt_pk_bf16_f32 v163, v122, v123
	v_cvt_pk_bf16_f32 v164, v124, v125
	v_cvt_pk_bf16_f32 v165, v126, v127
	v_pk_add_f32 v[128:129], v[128:129], v[120:121]
	v_pk_add_f32 v[128:129], v[128:129], v[122:123]
	v_pk_add_f32 v[128:129], v[128:129], v[124:125]
	v_pk_add_f32 v[128:129], v[128:129], v[126:127]
	v_mfma_f32_32x32x16_bf16 v[112:127], v[56:59], v[150:153], v[64:79]
	v_mfma_f32_32x32x16_bf16 v[112:127], v[60:63], v[154:157], v[112:127]
	s_waitcnt lgkmcnt(0)
	v_mfma_f32_32x32x16_bf16 v[0:15], v[162:165], v[192:195], v[0:15]
	v_mfma_f32_32x32x16_bf16 v[16:31], v[162:165], v[196:199], v[16:31]
	v_exp_f32_e32 v96, v96
	v_exp_f32_e32 v97, v97
	v_exp_f32_e32 v98, v98
	v_exp_f32_e32 v99, v99
	v_exp_f32_e32 v100, v100
	v_exp_f32_e32 v101, v101
	v_exp_f32_e32 v102, v102
	v_exp_f32_e32 v103, v103
	v_cvt_pk_bf16_f32 v162, v96, v97
	v_cvt_pk_bf16_f32 v163, v98, v99
	v_cvt_pk_bf16_f32 v164, v100, v101
	v_cvt_pk_bf16_f32 v165, v102, v103
	v_pk_add_f32 v[130:131], v[130:131], v[96:97]
	v_pk_add_f32 v[130:131], v[130:131], v[98:99]
	v_pk_add_f32 v[130:131], v[130:131], v[100:101]
	v_pk_add_f32 v[130:131], v[130:131], v[102:103]
	v_mfma_f32_32x32x16_bf16 v[80:95], v[162:165], v[168:171], v[80:95]
	v_exp_f32_e32 v104, v104
	v_exp_f32_e32 v105, v105
	v_exp_f32_e32 v106, v106
	v_exp_f32_e32 v107, v107
	v_mfma_f32_32x32x16_bf16 v[200:215], v[162:165], v[172:175], v[200:215]
	v_exp_f32_e32 v108, v108
	v_exp_f32_e32 v109, v109
	v_exp_f32_e32 v110, v110
	v_exp_f32_e32 v111, v111
	v_cvt_pk_bf16_f32 v162, v104, v105
	v_cvt_pk_bf16_f32 v163, v106, v107
	v_cvt_pk_bf16_f32 v164, v108, v109
	v_cvt_pk_bf16_f32 v165, v110, v111
	v_pk_add_f32 v[130:131], v[130:131], v[104:105]
	v_pk_add_f32 v[130:131], v[130:131], v[106:107]
	v_pk_add_f32 v[130:131], v[130:131], v[108:109]
	v_pk_add_f32 v[130:131], v[130:131], v[110:111]
	v_mfma_f32_32x32x16_bf16 v[80:95], v[162:165], v[176:179], v[80:95]
	v_exp_f32_e32 v112, v112
	v_exp_f32_e32 v113, v113
	v_exp_f32_e32 v114, v114
	v_exp_f32_e32 v115, v115
	v_mfma_f32_32x32x16_bf16 v[200:215], v[162:165], v[180:183], v[200:215]
	v_exp_f32_e32 v116, v116
	v_exp_f32_e32 v117, v117
	v_exp_f32_e32 v118, v118
	v_exp_f32_e32 v119, v119
	v_cvt_pk_bf16_f32 v162, v112, v113
	v_cvt_pk_bf16_f32 v163, v114, v115
	v_cvt_pk_bf16_f32 v164, v116, v117
	v_cvt_pk_bf16_f32 v165, v118, v119
	v_pk_add_f32 v[130:131], v[130:131], v[112:113]
	v_pk_add_f32 v[130:131], v[130:131], v[114:115]
	v_pk_add_f32 v[130:131], v[130:131], v[116:117]
	v_pk_add_f32 v[130:131], v[130:131], v[118:119]
	v_mfma_f32_32x32x16_bf16 v[80:95], v[162:165], v[184:187], v[80:95]
	v_exp_f32_e32 v120, v120
	v_exp_f32_e32 v121, v121
	v_exp_f32_e32 v122, v122
	v_exp_f32_e32 v123, v123
	v_mfma_f32_32x32x16_bf16 v[200:215], v[162:165], v[188:191], v[200:215]
	v_exp_f32_e32 v124, v124
	v_exp_f32_e32 v125, v125
	v_exp_f32_e32 v126, v126
	v_exp_f32_e32 v127, v127
	v_cvt_pk_bf16_f32 v162, v120, v121
	v_cvt_pk_bf16_f32 v163, v122, v123
	v_cvt_pk_bf16_f32 v164, v124, v125
	v_cvt_pk_bf16_f32 v165, v126, v127
	v_pk_add_f32 v[130:131], v[130:131], v[120:121]
	v_pk_add_f32 v[130:131], v[130:131], v[122:123]
	v_pk_add_f32 v[130:131], v[130:131], v[124:125]
	v_pk_add_f32 v[130:131], v[130:131], v[126:127]
	s_waitcnt vmcnt(4)
	s_waitcnt lgkmcnt(0)
	s_barrier
	s_cmp_eq_u32 s33, 21
	s_cbranch_scc1 .Lat_ndF1
; #define AT_LOAD(K0, K1, V0, V1, T) do { const size_t e_ = (size_t)(128 * (T) + sr) * 64 + sc; \
;         K0 = *(const bf16x8*)(kcp + e_); V0 = *(const bf16x8*)(vcp + e_); K1 = *(const bf16x8*)(kcp + e_ + 64 * 64); V1 = *(const bf16x8*)(vcp + e_ + 64 * 64); } while (0)
; #define AT_STORE(K0, K1, V0, V1, BUF) do { *(LAS bf16x8*)(lds + AT_K + (BUF) * AT_KB + kst0) = K0; *(LAS bf16x8*)(lds + AT_K + (BUF) * AT_KB + kst1) = K1; \
;         *(LAS bf16x8*)(lds + AT_V + (BUF) * AT_VB + vst0) = V0; *(LAS bf16x8*)(lds + AT_V + (BUF) * AT_VB + vst1) = V1; } while (0)
; template <int VAR>
; __device__ __forceinline__ void attn_unit(const Args& a, int l, int b, int h, int qrow0  , bool ctxu, const bf16* Z, bf16* Y, LAS unsigned char* lds) {
;     ...
;     for (int t = 0; t < NT; t += 2) {
;         __syncthreads();
;         if (t + 2 < NT) AT_LOAD(ka0, ka1, va0, va1, t + 2);
;         attn_tile(Kb0, vb0, q0, q1, negm, m, o0, o1, lacc, t == 0, wsf, r32, hi);
;         AT_STORE(kb0, kb1, vb0_, vb1_, 1);
;         __syncthreads();
;         if (t + 3 < NT) AT_LOAD(kb0, kb1, vb0_, vb1_, t + 3);
;         attn_tile(Kb0 + AT_KB, vb0 + AT_VB, q0, q1, negm, m, o0, o1, lacc, false, wsf, r32, hi);
;         if (t + 2 < NT) AT_STORE(ka0, ka1, va0, va1, 0);
;     }
.Lat_ndF1:
	ds_read_b128 v[48:51], v144 offset:16384
	ds_read_b128 v[52:55], v145 offset:16384
	ds_read_b128 v[56:59], v144 offset:20480
	ds_read_b128 v[60:63], v145 offset:20480
	v_mfma_f32_32x32x16_bf16 v[80:95], v[162:165], v[192:195], v[80:95]
	v_mfma_f32_32x32x16_bf16 v[200:215], v[162:165], v[196:199], v[200:215]
	s_waitcnt lgkmcnt(0)
	v_mfma_f32_32x32x16_bf16 v[96:111], v[48:51], v[136:139], v[32:47]
	ds_read_b64_tr_b16 v[168:169], v146 offset:16384
	ds_read_b64_tr_b16 v[170:171], v146 offset:17408
	ds_read_b64_tr_b16 v[172:173], v146 offset:16896
	ds_read_b64_tr_b16 v[174:175], v146 offset:17920
	v_mfma_f32_32x32x16_bf16 v[96:111], v[52:55], v[140:143], v[96:111]
	ds_read_b64_tr_b16 v[176:177], v146 offset:18432
	ds_read_b64_tr_b16 v[178:179], v146 offset:19456
	ds_read_b64_tr_b16 v[180:181], v146 offset:18944
	ds_read_b64_tr_b16 v[182:183], v146 offset:19968
	v_mfma_f32_32x32x16_bf16 v[112:127], v[56:59], v[136:139], v[32:47]
	ds_read_b64_tr_b16 v[184:185], v146 offset:20480
	ds_read_b64_tr_b16 v[186:187], v146 offset:21504
	ds_read_b64_tr_b16 v[188:189], v146 offset:20992
	ds_read_b64_tr_b16 v[190:191], v146 offset:22016
	v_mfma_f32_32x32x16_bf16 v[112:127], v[60:63], v[140:143], v[112:127]
	ds_read_b64_tr_b16 v[192:193], v146 offset:22528
	ds_read_b64_tr_b16 v[194:195], v146 offset:23552
	ds_read_b64_tr_b16 v[196:197], v146 offset:23040
	ds_read_b64_tr_b16 v[198:199], v146 offset:24064
	v_exp_f32_e32 v96, v96
	v_exp_f32_e32 v97, v97
	v_exp_f32_e32 v98, v98
	v_exp_f32_e32 v99, v99
	s_cmp_eq_u32 s33, 21
	s_cbranch_scc1 .Lat_dvF20
	s_add_u32 m0, s51, 0x0
	s_nop 0
	global_load_lds_dwordx4 v158, s[36:37]
.Lat_dvF20:
	v_exp_f32_e32 v100, v100
	v_exp_f32_e32 v101, v101
	v_exp_f32_e32 v102, v102
	v_exp_f32_e32 v103, v103
	s_cmp_eq_u32 s33, 21
	s_cbranch_scc1 .Lat_dvF21
	s_add_u32 m0, s51, 0x2000
	s_nop 0
	global_load_lds_dwordx4 v159, s[36:37]
	s_add_u32 s36, s36, 0x4000
	s_addc_u32 s37, s37, 0
.Lat_dvF21:
	v_cvt_pk_bf16_f32 v162, v96, v97
	v_cvt_pk_bf16_f32 v163, v98, v99
	v_cvt_pk_bf16_f32 v164, v100, v101
	v_cvt_pk_bf16_f32 v165, v102, v103
	v_pk_add_f32 v[128:129], v[128:129], v[96:97]
	v_pk_add_f32 v[128:129], v[128:129], v[98:99]
	v_pk_add_f32 v[128:129], v[128:129], v[100:101]
	v_pk_add_f32 v[128:129], v[128:129], v[102:103]
	s_waitcnt lgkmcnt(12)
	v_mfma_f32_32x32x16_bf16 v[0:15], v[162:165], v[168:171], v[0:15]
	v_exp_f32_e32 v104, v104
	v_exp_f32_e32 v105, v105
	v_exp_f32_e32 v106, v106
	v_exp_f32_e32 v107, v107
	v_mfma_f32_32x32x16_bf16 v[16:31], v[162:165], v[172:175], v[16:31]
	v_exp_f32_e32 v108, v108
	v_exp_f32_e32 v109, v109
	v_exp_f32_e32 v110, v110
	v_exp_f32_e32 v111, v111
	v_cvt_pk_bf16_f32 v162, v104, v105
	v_cvt_pk_bf16_f32 v163, v106, v107
	v_cvt_pk_bf16_f32 v164, v108, v109
	v_cvt_pk_bf16_f32 v165, v110, v111
	v_pk_add_f32 v[128:129], v[128:129], v[104:105]
	v_pk_add_f32 v[128:129], v[128:129], v[106:107]
	v_pk_add_f32 v[128:129], v[128:129], v[108:109]
	v_pk_add_f32 v[128:129], v[128:129], v[110:111]
	s_waitcnt lgkmcnt(8)
	v_mfma_f32_32x32x16_bf16 v[0:15], v[162:165], v[176:179], v[0:15]
	v_exp_f32_e32 v112, v112
	v_exp_f32_e32 v113, v113
	v_exp_f32_e32 v114, v114
	v_exp_f32_e32 v115, v115
	v_mfma_f32_32x32x16_bf16 v[16:31], v[162:165], v[180:183], v[16:31]
	v_mfma_f32_32x32x16_bf16 v[96:111], v[48:51], v[150:153], v[64:79]
	v_exp_f32_e32 v116, v116
	v_exp_f32_e32 v117, v117
	v_exp_f32_e32 v118, v118
	v_exp_f32_e32 v119, v119
	v_mfma_f32_32x32x16_bf16 v[96:111], v[52:55], v[154:157], v[96:111]
	v_cvt_pk_bf16_f32 v162, v112, v113
	v_cvt_pk_bf16_f32 v163, v114, v115
	v_cvt_pk_bf16_f32 v164, v116, v117
	v_cvt_pk_bf16_f32 v165, v118, v119
	v_pk_add_f32 v[128:129], v[128:129], v[112:113]
	v_pk_add_f32 v[128:129], v[128:129], v[114:115]
	v_pk_add_f32 v[128:129], v[128:129], v[116:117]
	v_pk_add_f32 v[128:129], v[128:129], v[118:119]
	s_waitcnt lgkmcnt(4)
	v_mfma_f32_32x32x16_bf16 v[0:15], v[162:165], v[184:187], v[0:15]
	v_exp_f32_e32 v120, v120
	v_exp_f32_e32 v121, v121
	v_exp_f32_e32 v122, v122
	v_exp_f32_e32 v123, v123
	v_mfma_f32_32x32x16_bf16 v[16:31], v[162:165], v[188:191], v[16:31]
	v_exp_f32_e32 v124, v124
	v_exp_f32_e32 v125, v125
	v_exp_f32_e32 v126, v126
	v_exp_f32_e32 v127, v127
	v_cvt_pk_bf16_f32 v162, v120, v121
	v_cvt_pk_bf16_f32 v163, v122, v123
	v_cvt_pk_bf16_f32 v164, v124, v125
	v_cvt_pk_bf16_f32 v165, v126, v127
	v_pk_add_f32 v[128:129], v[128:129], v[120:121]
	v_pk_add_f32 v[128:129], v[128:129], v[122:123]
	v_pk_add_f32 v[128:129], v[128:129], v[124:125]
	v_pk_add_f32 v[128:129], v[128:129], v[126:127]
	v_mfma_f32_32x32x16_bf16 v[112:127], v[56:59], v[150:153], v[64:79]
	v_mfma_f32_32x32x16_bf16 v[112:127], v[60:63], v[154:157], v[112:127]
	s_waitcnt lgkmcnt(0)
	v_mfma_f32_32x32x16_bf16 v[0:15], v[162:165], v[192:195], v[0:15]
	v_mfma_f32_32x32x16_bf16 v[16:31], v[162:165], v[196:199], v[16:31]
	ds_read_b128 v[48:51], v144 offset:24576
	ds_read_b128 v[52:55], v145 offset:24576
	ds_read_b128 v[56:59], v144 offset:28672
	ds_read_b128 v[60:63], v145 offset:28672
	v_exp_f32_e32 v96, v96
	v_exp_f32_e32 v97, v97
	v_exp_f32_e32 v98, v98
	v_exp_f32_e32 v99, v99
	s_cmp_eq_u32 s33, 21
	s_cbranch_scc1 .Lat_dvF22
	s_add_u32 m0, s51, 0xc000
	s_nop 0
	global_load_lds_dwordx4 v160, s[48:49]
.Lat_dvF22:
	v_exp_f32_e32 v100, v100
	v_exp_f32_e32 v101, v101
	v_exp_f32_e32 v102, v102
	v_exp_f32_e32 v103, v103
	s_cmp_eq_u32 s33, 21
	s_cbranch_scc1 .Lat_dvF23
	s_add_u32 m0, s51, 0xe000
	s_nop 0
	global_load_lds_dwordx4 v161, s[48:49]
	s_add_u32 s48, s48, 0x4000
	s_addc_u32 s49, s49, 0
.Lat_dvF23:
	v_cvt_pk_bf16_f32 v162, v96, v97
	v_cvt_pk_bf16_f32 v163, v98, v99
	v_cvt_pk_bf16_f32 v164, v100, v101
	v_cvt_pk_bf16_f32 v165, v102, v103
	v_pk_add_f32 v[130:131], v[130:131], v[96:97]
	v_pk_add_f32 v[130:131], v[130:131], v[98:99]
	v_pk_add_f32 v[130:131], v[130:131], v[100:101]
	v_pk_add_f32 v[130:131], v[130:131], v[102:103]
	v_mfma_f32_32x32x16_bf16 v[80:95], v[162:165], v[168:171], v[80:95]
	v_exp_f32_e32 v104, v104
	v_exp_f32_e32 v105, v105
	v_exp_f32_e32 v106, v106
	v_exp_f32_e32 v107, v107
	v_mfma_f32_32x32x16_bf16 v[200:215], v[162:165], v[172:175], v[200:215]
	v_exp_f32_e32 v108, v108
	v_exp_f32_e32 v109, v109
	v_exp_f32_e32 v110, v110
	v_exp_f32_e32 v111, v111
	v_cvt_pk_bf16_f32 v162, v104, v105
	v_cvt_pk_bf16_f32 v163, v106, v107
	v_cvt_pk_bf16_f32 v164, v108, v109
	v_cvt_pk_bf16_f32 v165, v110, v111
	v_pk_add_f32 v[130:131], v[130:131], v[104:105]
	v_pk_add_f32 v[130:131], v[130:131], v[106:107]
	v_pk_add_f32 v[130:131], v[130:131], v[108:109]
	v_pk_add_f32 v[130:131], v[130:131], v[110:111]
	v_mfma_f32_32x32x16_bf16 v[80:95], v[162:165], v[176:179], v[80:95]
	v_exp_f32_e32 v112, v112
	v_exp_f32_e32 v113, v113
	v_exp_f32_e32 v114, v114
	v_exp_f32_e32 v115, v115
	v_mfma_f32_32x32x16_bf16 v[200:215], v[162:165], v[180:183], v[200:215]
	v_exp_f32_e32 v116, v116
	v_exp_f32_e32 v117, v117
	v_exp_f32_e32 v118, v118
	v_exp_f32_e32 v119, v119
	v_cvt_pk_bf16_f32 v162, v112, v113
	v_cvt_pk_bf16_f32 v163, v114, v115
	v_cvt_pk_bf16_f32 v164, v116, v117
	v_cvt_pk_bf16_f32 v165, v118, v119
	v_pk_add_f32 v[130:131], v[130:131], v[112:113]
	v_pk_add_f32 v[130:131], v[130:131], v[114:115]
	v_pk_add_f32 v[130:131], v[130:131], v[116:117]
	v_pk_add_f32 v[130:131], v[130:131], v[118:119]
	v_mfma_f32_32x32x16_bf16 v[80:95], v[162:165], v[184:187], v[80:95]
	v_exp_f32_e32 v120, v120
	v_exp_f32_e32 v121, v121
	v_exp_f32_e32 v122, v122
	v_exp_f32_e32 v123, v123
	v_mfma_f32_32x32x16_bf16 v[200:215], v[162:165], v[188:191], v[200:215]
	v_exp_f32_e32 v124, v124
	v_exp_f32_e32 v125, v125
	v_exp_f32_e32 v126, v126
	v_exp_f32_e32 v127, v127
	v_cvt_pk_bf16_f32 v162, v120, v121
	v_cvt_pk_bf16_f32 v163, v122, v123
	v_cvt_pk_bf16_f32 v164, v124, v125
	v_cvt_pk_bf16_f32 v165, v126, v127
	v_pk_add_f32 v[130:131], v[130:131], v[120:121]
	v_pk_add_f32 v[130:131], v[130:131], v[122:123]
	v_pk_add_f32 v[130:131], v[130:131], v[124:125]
	v_pk_add_f32 v[130:131], v[130:131], v[126:127]
	v_mfma_f32_32x32x16_bf16 v[80:95], v[162:165], v[192:195], v[80:95]
	v_mfma_f32_32x32x16_bf16 v[200:215], v[162:165], v[196:199], v[200:215]
	s_waitcnt lgkmcnt(0)
	v_mfma_f32_32x32x16_bf16 v[96:111], v[48:51], v[136:139], v[32:47]
	ds_read_b64_tr_b16 v[168:169], v146 offset:24576
	ds_read_b64_tr_b16 v[170:171], v146 offset:25600
	ds_read_b64_tr_b16 v[172:173], v146 offset:25088
	ds_read_b64_tr_b16 v[174:175], v146 offset:26112
	v_mfma_f32_32x32x16_bf16 v[96:111], v[52:55], v[140:143], v[96:111]
	ds_read_b64_tr_b16 v[176:177], v146 offset:26624
	ds_read_b64_tr_b16 v[178:179], v146 offset:27648
	ds_read_b64_tr_b16 v[180:181], v146 offset:27136
	ds_read_b64_tr_b16 v[182:183], v146 offset:28160
	v_mfma_f32_32x32x16_bf16 v[112:127], v[56:59], v[136:139], v[32:47]
	ds_read_b64_tr_b16 v[184:185], v146 offset:28672
	ds_read_b64_tr_b16 v[186:187], v146 offset:29696
	ds_read_b64_tr_b16 v[188:189], v146 offset:29184
	ds_read_b64_tr_b16 v[190:191], v146 offset:30208
	v_mfma_f32_32x32x16_bf16 v[112:127], v[60:63], v[140:143], v[112:127]
	ds_read_b64_tr_b16 v[192:193], v146 offset:30720
	ds_read_b64_tr_b16 v[194:195], v146 offset:31744
	ds_read_b64_tr_b16 v[196:197], v146 offset:31232
	ds_read_b64_tr_b16 v[198:199], v146 offset:32256
	v_exp_f32_e32 v96, v96
	v_exp_f32_e32 v97, v97
	v_exp_f32_e32 v98, v98
	v_exp_f32_e32 v99, v99
	v_exp_f32_e32 v100, v100
	v_exp_f32_e32 v101, v101
	v_exp_f32_e32 v102, v102
	v_exp_f32_e32 v103, v103
	v_cvt_pk_bf16_f32 v162, v96, v97
	v_cvt_pk_bf16_f32 v163, v98, v99
	v_cvt_pk_bf16_f32 v164, v100, v101
	v_cvt_pk_bf16_f32 v165, v102, v103
	v_pk_add_f32 v[128:129], v[128:129], v[96:97]
	v_pk_add_f32 v[128:129], v[128:129], v[98:99]
	v_pk_add_f32 v[128:129], v[128:129], v[100:101]
	v_pk_add_f32 v[128:129], v[128:129], v[102:103]
	s_waitcnt lgkmcnt(12)
	v_mfma_f32_32x32x16_bf16 v[0:15], v[162:165], v[168:171], v[0:15]
	v_exp_f32_e32 v104, v104
	v_exp_f32_e32 v105, v105
	v_exp_f32_e32 v106, v106
	v_exp_f32_e32 v107, v107
	v_mfma_f32_32x32x16_bf16 v[16:31], v[162:165], v[172:175], v[16:31]
	v_exp_f32_e32 v108, v108
	v_exp_f32_e32 v109, v109
	v_exp_f32_e32 v110, v110
	v_exp_f32_e32 v111, v111
	v_cvt_pk_bf16_f32 v162, v104, v105
	v_cvt_pk_bf16_f32 v163, v106, v107
	v_cvt_pk_bf16_f32 v164, v108, v109
	v_cvt_pk_bf16_f32 v165, v110, v111
	v_pk_add_f32 v[128:129], v[128:129], v[104:105]
	v_pk_add_f32 v[128:129], v[128:129], v[106:107]
	v_pk_add_f32 v[128:129], v[128:129], v[108:109]
	v_pk_add_f32 v[128:129], v[128:129], v[110:111]
	s_waitcnt lgkmcnt(8)
	v_mfma_f32_32x32x16_bf16 v[0:15], v[162:165], v[176:179], v[0:15]
	v_exp_f32_e32 v112, v112
	v_exp_f32_e32 v113, v113
	v_exp_f32_e32 v114, v114
	v_exp_f32_e32 v115, v115
	v_mfma_f32_32x32x16_bf16 v[16:31], v[162:165], v[180:183], v[16:31]
	v_mfma_f32_32x32x16_bf16 v[96:111], v[48:51], v[150:153], v[64:79]
	v_exp_f32_e32 v116, v116
	v_exp_f32_e32 v117, v117
	v_exp_f32_e32 v118, v118
	v_exp_f32_e32 v119, v119
	v_mfma_f32_32x32x16_bf16 v[96:111], v[52:55], v[154:157], v[96:111]
	v_cvt_pk_bf16_f32 v162, v112, v113
	v_cvt_pk_bf16_f32 v163, v114, v115
	v_cvt_pk_bf16_f32 v164, v116, v117
	v_cvt_pk_bf16_f32 v165, v118, v119
	v_pk_add_f32 v[128:129], v[128:129], v[112:113]
	v_pk_add_f32 v[128:129], v[128:129], v[114:115]
	v_pk_add_f32 v[128:129], v[128:129], v[116:117]
	v_pk_add_f32 v[128:129], v[128:129], v[118:119]
	s_waitcnt lgkmcnt(4)
	v_mfma_f32_32x32x16_bf16 v[0:15], v[162:165], v[184:187], v[0:15]
	v_exp_f32_e32 v120, v120
	v_exp_f32_e32 v121, v121
	v_exp_f32_e32 v122, v122
	v_exp_f32_e32 v123, v123
	v_mfma_f32_32x32x16_bf16 v[16:31], v[162:165], v[188:191], v[16:31]
	v_exp_f32_e32 v124, v124
	v_exp_f32_e32 v125, v125
	v_exp_f32_e32 v126, v126
	v_exp_f32_e32 v127, v127
	v_cvt_pk_bf16_f32 v162, v120, v121
	v_cvt_pk_bf16_f32 v163, v122, v123
	v_cvt_pk_bf16_f32 v164, v124, v125
	v_cvt_pk_bf16_f32 v165, v126, v127
	v_pk_add_f32 v[128:129], v[128:129], v[120:121]
	v_pk_add_f32 v[128:129], v[128:129], v[122:123]
	v_pk_add_f32 v[128:129], v[128:129], v[124:125]
	v_pk_add_f32 v[128:129], v[128:129], v[126:127]
	v_mfma_f32_32x32x16_bf16 v[112:127], v[56:59], v[150:153], v[64:79]
	v_mfma_f32_32x32x16_bf16 v[112:127], v[60:63], v[154:157], v[112:127]
	s_waitcnt lgkmcnt(0)
	v_mfma_f32_32x32x16_bf16 v[0:15], v[162:165], v[192:195], v[0:15]
	v_mfma_f32_32x32x16_bf16 v[16:31], v[162:165], v[196:199], v[16:31]
	v_exp_f32_e32 v96, v96
	v_exp_f32_e32 v97, v97
	v_exp_f32_e32 v98, v98
	v_exp_f32_e32 v99, v99
	v_exp_f32_e32 v100, v100
	v_exp_f32_e32 v101, v101
	v_exp_f32_e32 v102, v102
	v_exp_f32_e32 v103, v103
	v_cvt_pk_bf16_f32 v162, v96, v97
	v_cvt_pk_bf16_f32 v163, v98, v99
	v_cvt_pk_bf16_f32 v164, v100, v101
	v_cvt_pk_bf16_f32 v165, v102, v103
	v_pk_add_f32 v[130:131], v[130:131], v[96:97]
	v_pk_add_f32 v[130:131], v[130:131], v[98:99]
	v_pk_add_f32 v[130:131], v[130:131], v[100:101]
	v_pk_add_f32 v[130:131], v[130:131], v[102:103]
	v_mfma_f32_32x32x16_bf16 v[80:95], v[162:165], v[168:171], v[80:95]
	v_exp_f32_e32 v104, v104
	v_exp_f32_e32 v105, v105
	v_exp_f32_e32 v106, v106
	v_exp_f32_e32 v107, v107
	v_mfma_f32_32x32x16_bf16 v[200:215], v[162:165], v[172:175], v[200:215]
	v_exp_f32_e32 v108, v108
	v_exp_f32_e32 v109, v109
	v_exp_f32_e32 v110, v110
	v_exp_f32_e32 v111, v111
	v_cvt_pk_bf16_f32 v162, v104, v105
	v_cvt_pk_bf16_f32 v163, v106, v107
	v_cvt_pk_bf16_f32 v164, v108, v109
	v_cvt_pk_bf16_f32 v165, v110, v111
	v_pk_add_f32 v[130:131], v[130:131], v[104:105]
	v_pk_add_f32 v[130:131], v[130:131], v[106:107]
	v_pk_add_f32 v[130:131], v[130:131], v[108:109]
	v_pk_add_f32 v[130:131], v[130:131], v[110:111]
	v_mfma_f32_32x32x16_bf16 v[80:95], v[162:165], v[176:179], v[80:95]
	v_exp_f32_e32 v112, v112
	v_exp_f32_e32 v113, v113
	v_exp_f32_e32 v114, v114
	v_exp_f32_e32 v115, v115
	v_mfma_f32_32x32x16_bf16 v[200:215], v[162:165], v[180:183], v[200:215]
	v_exp_f32_e32 v116, v116
	v_exp_f32_e32 v117, v117
	v_exp_f32_e32 v118, v118
	v_exp_f32_e32 v119, v119
	v_cvt_pk_bf16_f32 v162, v112, v113
	v_cvt_pk_bf16_f32 v163, v114, v115
	v_cvt_pk_bf16_f32 v164, v116, v117
	v_cvt_pk_bf16_f32 v165, v118, v119
	v_pk_add_f32 v[130:131], v[130:131], v[112:113]
	v_pk_add_f32 v[130:131], v[130:131], v[114:115]
	v_pk_add_f32 v[130:131], v[130:131], v[116:117]
	v_pk_add_f32 v[130:131], v[130:131], v[118:119]
	v_mfma_f32_32x32x16_bf16 v[80:95], v[162:165], v[184:187], v[80:95]
	v_exp_f32_e32 v120, v120
	v_exp_f32_e32 v121, v121
	v_exp_f32_e32 v122, v122
	v_exp_f32_e32 v123, v123
	v_mfma_f32_32x32x16_bf16 v[200:215], v[162:165], v[188:191], v[200:215]
	v_exp_f32_e32 v124, v124
	v_exp_f32_e32 v125, v125
	v_exp_f32_e32 v126, v126
	v_exp_f32_e32 v127, v127
	v_cvt_pk_bf16_f32 v162, v120, v121
	v_cvt_pk_bf16_f32 v163, v122, v123
	v_cvt_pk_bf16_f32 v164, v124, v125
	v_cvt_pk_bf16_f32 v165, v126, v127
	v_pk_add_f32 v[130:131], v[130:131], v[120:121]
	v_pk_add_f32 v[130:131], v[130:131], v[122:123]
	v_pk_add_f32 v[130:131], v[130:131], v[124:125]
	v_pk_add_f32 v[130:131], v[130:131], v[126:127]
	s_cmp_eq_u32 s33, 21
	s_cbranch_scc1 .Lat_w0F3
	s_waitcnt vmcnt(4)
	s_branch .Lat_wdF3

; #define AT_LOAD(K0, K1, V0, V1, T) do { const size_t e_ = (size_t)(128 * (T) + sr) * 64 + sc; \
;         K0 = *(const bf16x8*)(kcp + e_); V0 = *(const bf16x8*)(vcp + e_); K1 = *(const bf16x8*)(kcp + e_ + 64 * 64); V1 = *(const bf16x8*)(vcp + e_ + 64 * 64); } while (0)
; #define AT_STORE(K0, K1, V0, V1, BUF) do { *(LAS bf16x8*)(lds + AT_K + (BUF) * AT_KB + kst0) = K0; *(LAS bf16x8*)(lds + AT_K + (BUF) * AT_KB + kst1) = K1; \
;         *(LAS bf16x8*)(lds + AT_V + (BUF) * AT_VB + vst0) = V0; *(LAS bf16x8*)(lds + AT_V + (BUF) * AT_VB + vst1) = V1; } while (0)
; template <int VAR>
; __device__ __forceinline__ void attn_unit(const Args& a, int l, int b, int h, int qrow0  , bool ctxu, const bf16* Z, bf16* Y, LAS unsigned char* lds) {
;     ...
;     for (int t = 0; t < NT; t += 2) {
;         __syncthreads();
;         if (t + 2 < NT) AT_LOAD(ka0, ka1, va0, va1, t + 2);
;         attn_tile(Kb0, vb0, q0, q1, negm, m, o0, o1, lacc, t == 0, wsf, r32, hi);
;         AT_STORE(kb0, kb1, vb0_, vb1_, 1);
;         __syncthreads();
;         if (t + 3 < NT) AT_LOAD(kb0, kb1, vb0_, vb1_, t + 3);
;         attn_tile(Kb0 + AT_KB, vb0 + AT_VB, q0, q1, negm, m, o0, o1, lacc, false, wsf, r32, hi);
;         if (t + 2 < NT) AT_STORE(ka0, ka1, va0, va1, 0);
;     }
.Lat_ndF3:
	ds_read_b128 v[48:51], v144 offset:32768
	ds_read_b128 v[52:55], v145 offset:32768
	ds_read_b128 v[56:59], v144 offset:36864
	ds_read_b128 v[60:63], v145 offset:36864
	v_mfma_f32_32x32x16_bf16 v[80:95], v[162:165], v[192:195], v[80:95]
	v_mfma_f32_32x32x16_bf16 v[200:215], v[162:165], v[196:199], v[200:215]
	s_waitcnt lgkmcnt(0)
	v_mfma_f32_32x32x16_bf16 v[96:111], v[48:51], v[136:139], v[32:47]
	ds_read_b64_tr_b16 v[168:169], v146 offset:32768
	ds_read_b64_tr_b16 v[170:171], v146 offset:33792
	ds_read_b64_tr_b16 v[172:173], v146 offset:33280
	ds_read_b64_tr_b16 v[174:175], v146 offset:34304
	v_mfma_f32_32x32x16_bf16 v[96:111], v[52:55], v[140:143], v[96:111]
	ds_read_b64_tr_b16 v[176:177], v146 offset:34816
	ds_read_b64_tr_b16 v[178:179], v146 offset:35840
	ds_read_b64_tr_b16 v[180:181], v146 offset:35328
	ds_read_b64_tr_b16 v[182:183], v146 offset:36352
	v_mfma_f32_32x32x16_bf16 v[112:127], v[56:59], v[136:139], v[32:47]
	ds_read_b64_tr_b16 v[184:185], v146 offset:36864
	ds_read_b64_tr_b16 v[186:187], v146 offset:37888
	ds_read_b64_tr_b16 v[188:189], v146 offset:37376
	ds_read_b64_tr_b16 v[190:191], v146 offset:38400
	v_mfma_f32_32x32x16_bf16 v[112:127], v[60:63], v[140:143], v[112:127]
	ds_read_b64_tr_b16 v[192:193], v146 offset:38912
	ds_read_b64_tr_b16 v[194:195], v146 offset:39936
	ds_read_b64_tr_b16 v[196:197], v146 offset:39424
	ds_read_b64_tr_b16 v[198:199], v146 offset:40448
	v_exp_f32_e32 v96, v96
	v_exp_f32_e32 v97, v97
	v_exp_f32_e32 v98, v98
	v_exp_f32_e32 v99, v99
	s_cmp_eq_u32 s33, 21
	s_cbranch_scc1 .Lat_dvF40
	s_add_u32 m0, s51, 0x4000
	s_nop 0
	global_load_lds_dwordx4 v158, s[36:37]
.Lat_dvF40:
	v_exp_f32_e32 v100, v100
	v_exp_f32_e32 v101, v101
	v_exp_f32_e32 v102, v102
	v_exp_f32_e32 v103, v103
	s_cmp_eq_u32 s33, 21
	s_cbranch_scc1 .Lat_dvF41
	s_add_u32 m0, s51, 0x6000
	s_nop 0
	global_load_lds_dwordx4 v159, s[36:37]
	s_add_u32 s36, s36, 0x4000
	s_addc_u32 s37, s37, 0
.Lat_dvF41:
	v_cvt_pk_bf16_f32 v162, v96, v97
	v_cvt_pk_bf16_f32 v163, v98, v99
	v_cvt_pk_bf16_f32 v164, v100, v101
	v_cvt_pk_bf16_f32 v165, v102, v103
	v_pk_add_f32 v[128:129], v[128:129], v[96:97]
	v_pk_add_f32 v[128:129], v[128:129], v[98:99]
	v_pk_add_f32 v[128:129], v[128:129], v[100:101]
	v_pk_add_f32 v[128:129], v[128:129], v[102:103]
	s_waitcnt lgkmcnt(12)
	v_mfma_f32_32x32x16_bf16 v[0:15], v[162:165], v[168:171], v[0:15]
	v_exp_f32_e32 v104, v104
	v_exp_f32_e32 v105, v105
	v_exp_f32_e32 v106, v106
	v_exp_f32_e32 v107, v107
	v_mfma_f32_32x32x16_bf16 v[16:31], v[162:165], v[172:175], v[16:31]
	v_exp_f32_e32 v108, v108
	v_exp_f32_e32 v109, v109
	v_exp_f32_e32 v110, v110
	v_exp_f32_e32 v111, v111
	v_cvt_pk_bf16_f32 v162, v104, v105
	v_cvt_pk_bf16_f32 v163, v106, v107
	v_cvt_pk_bf16_f32 v164, v108, v109
	v_cvt_pk_bf16_f32 v165, v110, v111
	v_pk_add_f32 v[128:129], v[128:129], v[104:105]
	v_pk_add_f32 v[128:129], v[128:129], v[106:107]
	v_pk_add_f32 v[128:129], v[128:129], v[108:109]
	v_pk_add_f32 v[128:129], v[128:129], v[110:111]
	s_waitcnt lgkmcnt(8)
	v_mfma_f32_32x32x16_bf16 v[0:15], v[162:165], v[176:179], v[0:15]
	v_exp_f32_e32 v112, v112
	v_exp_f32_e32 v113, v113
	v_exp_f32_e32 v114, v114
	v_exp_f32_e32 v115, v115
	v_mfma_f32_32x32x16_bf16 v[16:31], v[162:165], v[180:183], v[16:31]
	v_mfma_f32_32x32x16_bf16 v[96:111], v[48:51], v[150:153], v[64:79]
	v_exp_f32_e32 v116, v116
	v_exp_f32_e32 v117, v117
	v_exp_f32_e32 v118, v118
	v_exp_f32_e32 v119, v119
	v_mfma_f32_32x32x16_bf16 v[96:111], v[52:55], v[154:157], v[96:111]
	v_cvt_pk_bf16_f32 v162, v112, v113
	v_cvt_pk_bf16_f32 v163, v114, v115
	v_cvt_pk_bf16_f32 v164, v116, v117
	v_cvt_pk_bf16_f32 v165, v118, v119
	v_pk_add_f32 v[128:129], v[128:129], v[112:113]
	v_pk_add_f32 v[128:129], v[128:129], v[114:115]
	v_pk_add_f32 v[128:129], v[128:129], v[116:117]
	v_pk_add_f32 v[128:129], v[128:129], v[118:119]
	s_waitcnt lgkmcnt(4)
	v_mfma_f32_32x32x16_bf16 v[0:15], v[162:165], v[184:187], v[0:15]
	v_exp_f32_e32 v120, v120
	v_exp_f32_e32 v121, v121
	v_exp_f32_e32 v122, v122
	v_exp_f32_e32 v123, v123
	v_mfma_f32_32x32x16_bf16 v[16:31], v[162:165], v[188:191], v[16:31]
	v_exp_f32_e32 v124, v124
	v_exp_f32_e32 v125, v125
	v_exp_f32_e32 v126, v126
	v_exp_f32_e32 v127, v127
	v_cvt_pk_bf16_f32 v162, v120, v121
	v_cvt_pk_bf16_f32 v163, v122, v123
	v_cvt_pk_bf16_f32 v164, v124, v125
	v_cvt_pk_bf16_f32 v165, v126, v127
	v_pk_add_f32 v[128:129], v[128:129], v[120:121]
	v_pk_add_f32 v[128:129], v[128:129], v[122:123]
	v_pk_add_f32 v[128:129], v[128:129], v[124:125]
	v_pk_add_f32 v[128:129], v[128:129], v[126:127]
	v_mfma_f32_32x32x16_bf16 v[112:127], v[56:59], v[150:153], v[64:79]
	v_mfma_f32_32x32x16_bf16 v[112:127], v[60:63], v[154:157], v[112:127]
	s_waitcnt lgkmcnt(0)
	v_mfma_f32_32x32x16_bf16 v[0:15], v[162:165], v[192:195], v[0:15]
	v_mfma_f32_32x32x16_bf16 v[16:31], v[162:165], v[196:199], v[16:31]
	ds_read_b128 v[48:51], v144 offset:40960
	ds_read_b128 v[52:55], v145 offset:40960
	ds_read_b128 v[56:59], v144 offset:45056
	ds_read_b128 v[60:63], v145 offset:45056
	v_exp_f32_e32 v96, v96
	v_exp_f32_e32 v97, v97
	v_exp_f32_e32 v98, v98
	v_exp_f32_e32 v99, v99
	s_cmp_eq_u32 s33, 21
	s_cbranch_scc1 .Lat_dvF42
	s_add_u32 m0, s51, 0x10000
	s_nop 0
	global_load_lds_dwordx4 v160, s[48:49]
.Lat_dvF42:
	v_exp_f32_e32 v100, v100
	v_exp_f32_e32 v101, v101
	v_exp_f32_e32 v102, v102
	v_exp_f32_e32 v103, v103
	s_cmp_eq_u32 s33, 21
	s_cbranch_scc1 .Lat_dvF43
	s_add_u32 m0, s51, 0x12000
	s_nop 0
	global_load_lds_dwordx4 v161, s[48:49]
	s_add_u32 s48, s48, 0x4000
	s_addc_u32 s49, s49, 0
.Lat_dvF43:
	v_cvt_pk_bf16_f32 v162, v96, v97
	v_cvt_pk_bf16_f32 v163, v98, v99
	v_cvt_pk_bf16_f32 v164, v100, v101
	v_cvt_pk_bf16_f32 v165, v102, v103
	v_pk_add_f32 v[130:131], v[130:131], v[96:97]
	v_pk_add_f32 v[130:131], v[130:131], v[98:99]
	v_pk_add_f32 v[130:131], v[130:131], v[100:101]
	v_pk_add_f32 v[130:131], v[130:131], v[102:103]
	v_mfma_f32_32x32x16_bf16 v[80:95], v[162:165], v[168:171], v[80:95]
	v_exp_f32_e32 v104, v104
	v_exp_f32_e32 v105, v105
	v_exp_f32_e32 v106, v106
	v_exp_f32_e32 v107, v107
	v_mfma_f32_32x32x16_bf16 v[200:215], v[162:165], v[172:175], v[200:215]
	v_exp_f32_e32 v108, v108
	v_exp_f32_e32 v109, v109
	v_exp_f32_e32 v110, v110
	v_exp_f32_e32 v111, v111
	v_cvt_pk_bf16_f32 v162, v104, v105
	v_cvt_pk_bf16_f32 v163, v106, v107
	v_cvt_pk_bf16_f32 v164, v108, v109
	v_cvt_pk_bf16_f32 v165, v110, v111
	v_pk_add_f32 v[130:131], v[130:131], v[104:105]
	v_pk_add_f32 v[130:131], v[130:131], v[106:107]
	v_pk_add_f32 v[130:131], v[130:131], v[108:109]
	v_pk_add_f32 v[130:131], v[130:131], v[110:111]
	v_mfma_f32_32x32x16_bf16 v[80:95], v[162:165], v[176:179], v[80:95]
	v_exp_f32_e32 v112, v112
	v_exp_f32_e32 v113, v113
	v_exp_f32_e32 v114, v114
	v_exp_f32_e32 v115, v115
	v_mfma_f32_32x32x16_bf16 v[200:215], v[162:165], v[180:183], v[200:215]
	v_exp_f32_e32 v116, v116
	v_exp_f32_e32 v117, v117
	v_exp_f32_e32 v118, v118
	v_exp_f32_e32 v119, v119
	v_cvt_pk_bf16_f32 v162, v112, v113
	v_cvt_pk_bf16_f32 v163, v114, v115
	v_cvt_pk_bf16_f32 v164, v116, v117
	v_cvt_pk_bf16_f32 v165, v118, v119
	v_pk_add_f32 v[130:131], v[130:131], v[112:113]
	v_pk_add_f32 v[130:131], v[130:131], v[114:115]
	v_pk_add_f32 v[130:131], v[130:131], v[116:117]
	v_pk_add_f32 v[130:131], v[130:131], v[118:119]
	v_mfma_f32_32x32x16_bf16 v[80:95], v[162:165], v[184:187], v[80:95]
	v_exp_f32_e32 v120, v120
	v_exp_f32_e32 v121, v121
	v_exp_f32_e32 v122, v122
	v_exp_f32_e32 v123, v123
	v_mfma_f32_32x32x16_bf16 v[200:215], v[162:165], v[188:191], v[200:215]
	v_exp_f32_e32 v124, v124
	v_exp_f32_e32 v125, v125
	v_exp_f32_e32 v126, v126
	v_exp_f32_e32 v127, v127
	v_cvt_pk_bf16_f32 v162, v120, v121
	v_cvt_pk_bf16_f32 v163, v122, v123
	v_cvt_pk_bf16_f32 v164, v124, v125
	v_cvt_pk_bf16_f32 v165, v126, v127
	v_pk_add_f32 v[130:131], v[130:131], v[120:121]
	v_pk_add_f32 v[130:131], v[130:131], v[122:123]
	v_pk_add_f32 v[130:131], v[130:131], v[124:125]
	v_pk_add_f32 v[130:131], v[130:131], v[126:127]
	v_mfma_f32_32x32x16_bf16 v[80:95], v[162:165], v[192:195], v[80:95]
	v_mfma_f32_32x32x16_bf16 v[200:215], v[162:165], v[196:199], v[200:215]
	s_waitcnt lgkmcnt(0)
	v_mfma_f32_32x32x16_bf16 v[96:111], v[48:51], v[136:139], v[32:47]
	ds_read_b64_tr_b16 v[168:169], v146 offset:40960
	ds_read_b64_tr_b16 v[170:171], v146 offset:41984
	ds_read_b64_tr_b16 v[172:173], v146 offset:41472
	ds_read_b64_tr_b16 v[174:175], v146 offset:42496
	v_mfma_f32_32x32x16_bf16 v[96:111], v[52:55], v[140:143], v[96:111]
	ds_read_b64_tr_b16 v[176:177], v146 offset:43008
	ds_read_b64_tr_b16 v[178:179], v146 offset:44032
	ds_read_b64_tr_b16 v[180:181], v146 offset:43520
	ds_read_b64_tr_b16 v[182:183], v146 offset:44544
	v_mfma_f32_32x32x16_bf16 v[112:127], v[56:59], v[136:139], v[32:47]
	ds_read_b64_tr_b16 v[184:185], v146 offset:45056
	ds_read_b64_tr_b16 v[186:187], v146 offset:46080
	ds_read_b64_tr_b16 v[188:189], v146 offset:45568
	ds_read_b64_tr_b16 v[190:191], v146 offset:46592
	v_mfma_f32_32x32x16_bf16 v[112:127], v[60:63], v[140:143], v[112:127]
	ds_read_b64_tr_b16 v[192:193], v146 offset:47104
	ds_read_b64_tr_b16 v[194:195], v146 offset:48128
	ds_read_b64_tr_b16 v[196:197], v146 offset:47616
	ds_read_b64_tr_b16 v[198:199], v146 offset:48640
	v_exp_f32_e32 v96, v96
	v_exp_f32_e32 v97, v97
	v_exp_f32_e32 v98, v98
	v_exp_f32_e32 v99, v99
	v_exp_f32_e32 v100, v100
	v_exp_f32_e32 v101, v101
	v_exp_f32_e32 v102, v102
	v_exp_f32_e32 v103, v103
	v_cvt_pk_bf16_f32 v162, v96, v97
	v_cvt_pk_bf16_f32 v163, v98, v99
	v_cvt_pk_bf16_f32 v164, v100, v101
	v_cvt_pk_bf16_f32 v165, v102, v103
	v_pk_add_f32 v[128:129], v[128:129], v[96:97]
	v_pk_add_f32 v[128:129], v[128:129], v[98:99]
	v_pk_add_f32 v[128:129], v[128:129], v[100:101]
	v_pk_add_f32 v[128:129], v[128:129], v[102:103]
	s_waitcnt lgkmcnt(12)
	v_mfma_f32_32x32x16_bf16 v[0:15], v[162:165], v[168:171], v[0:15]
	v_exp_f32_e32 v104, v104
	v_exp_f32_e32 v105, v105
	v_exp_f32_e32 v106, v106
	v_exp_f32_e32 v107, v107
	v_mfma_f32_32x32x16_bf16 v[16:31], v[162:165], v[172:175], v[16:31]
	v_exp_f32_e32 v108, v108
	v_exp_f32_e32 v109, v109
	v_exp_f32_e32 v110, v110
	v_exp_f32_e32 v111, v111
	v_cvt_pk_bf16_f32 v162, v104, v105
	v_cvt_pk_bf16_f32 v163, v106, v107
	v_cvt_pk_bf16_f32 v164, v108, v109
	v_cvt_pk_bf16_f32 v165, v110, v111
	v_pk_add_f32 v[128:129], v[128:129], v[104:105]
	v_pk_add_f32 v[128:129], v[128:129], v[106:107]
	v_pk_add_f32 v[128:129], v[128:129], v[108:109]
	v_pk_add_f32 v[128:129], v[128:129], v[110:111]
	s_waitcnt lgkmcnt(8)
	v_mfma_f32_32x32x16_bf16 v[0:15], v[162:165], v[176:179], v[0:15]
	v_exp_f32_e32 v112, v112
	v_exp_f32_e32 v113, v113
	v_exp_f32_e32 v114, v114
	v_exp_f32_e32 v115, v115
	v_mfma_f32_32x32x16_bf16 v[16:31], v[162:165], v[180:183], v[16:31]
	v_mfma_f32_32x32x16_bf16 v[96:111], v[48:51], v[150:153], v[64:79]
	v_exp_f32_e32 v116, v116
	v_exp_f32_e32 v117, v117
	v_exp_f32_e32 v118, v118
	v_exp_f32_e32 v119, v119
	v_mfma_f32_32x32x16_bf16 v[96:111], v[52:55], v[154:157], v[96:111]
	v_cvt_pk_bf16_f32 v162, v112, v113
	v_cvt_pk_bf16_f32 v163, v114, v115
	v_cvt_pk_bf16_f32 v164, v116, v117
	v_cvt_pk_bf16_f32 v165, v118, v119
	v_pk_add_f32 v[128:129], v[128:129], v[112:113]
	v_pk_add_f32 v[128:129], v[128:129], v[114:115]
	v_pk_add_f32 v[128:129], v[128:129], v[116:117]
	v_pk_add_f32 v[128:129], v[128:129], v[118:119]
	s_waitcnt lgkmcnt(4)
	v_mfma_f32_32x32x16_bf16 v[0:15], v[162:165], v[184:187], v[0:15]
	v_exp_f32_e32 v120, v120
	v_exp_f32_e32 v121, v121
	v_exp_f32_e32 v122, v122
	v_exp_f32_e32 v123, v123
	v_mfma_f32_32x32x16_bf16 v[16:31], v[162:165], v[188:191], v[16:31]
	v_exp_f32_e32 v124, v124
	v_exp_f32_e32 v125, v125
	v_exp_f32_e32 v126, v126
	v_exp_f32_e32 v127, v127
	v_cvt_pk_bf16_f32 v162, v120, v121
	v_cvt_pk_bf16_f32 v163, v122, v123
	v_cvt_pk_bf16_f32 v164, v124, v125
	v_cvt_pk_bf16_f32 v165, v126, v127
	v_pk_add_f32 v[128:129], v[128:129], v[120:121]
	v_pk_add_f32 v[128:129], v[128:129], v[122:123]
	v_pk_add_f32 v[128:129], v[128:129], v[124:125]
	v_pk_add_f32 v[128:129], v[128:129], v[126:127]
	v_mfma_f32_32x32x16_bf16 v[112:127], v[56:59], v[150:153], v[64:79]
	v_mfma_f32_32x32x16_bf16 v[112:127], v[60:63], v[154:157], v[112:127]
	s_waitcnt lgkmcnt(0)
	v_mfma_f32_32x32x16_bf16 v[0:15], v[162:165], v[192:195], v[0:15]
	v_mfma_f32_32x32x16_bf16 v[16:31], v[162:165], v[196:199], v[16:31]
	v_exp_f32_e32 v96, v96
	v_exp_f32_e32 v97, v97
	v_exp_f32_e32 v98, v98
	v_exp_f32_e32 v99, v99
	v_exp_f32_e32 v100, v100
	v_exp_f32_e32 v101, v101
	v_exp_f32_e32 v102, v102
	v_exp_f32_e32 v103, v103
	v_cvt_pk_bf16_f32 v162, v96, v97
	v_cvt_pk_bf16_f32 v163, v98, v99
	v_cvt_pk_bf16_f32 v164, v100, v101
	v_cvt_pk_bf16_f32 v165, v102, v103
	v_pk_add_f32 v[130:131], v[130:131], v[96:97]
	v_pk_add_f32 v[130:131], v[130:131], v[98:99]
	v_pk_add_f32 v[130:131], v[130:131], v[100:101]
	v_pk_add_f32 v[130:131], v[130:131], v[102:103]
	v_mfma_f32_32x32x16_bf16 v[80:95], v[162:165], v[168:171], v[80:95]
	v_exp_f32_e32 v104, v104
	v_exp_f32_e32 v105, v105
	v_exp_f32_e32 v106, v106
	v_exp_f32_e32 v107, v107
	v_mfma_f32_32x32x16_bf16 v[200:215], v[162:165], v[172:175], v[200:215]
	v_exp_f32_e32 v108, v108
	v_exp_f32_e32 v109, v109
	v_exp_f32_e32 v110, v110
	v_exp_f32_e32 v111, v111
	v_cvt_pk_bf16_f32 v162, v104, v105
	v_cvt_pk_bf16_f32 v163, v106, v107
	v_cvt_pk_bf16_f32 v164, v108, v109
	v_cvt_pk_bf16_f32 v165, v110, v111
	v_pk_add_f32 v[130:131], v[130:131], v[104:105]
	v_pk_add_f32 v[130:131], v[130:131], v[106:107]
	v_pk_add_f32 v[130:131], v[130:131], v[108:109]
	v_pk_add_f32 v[130:131], v[130:131], v[110:111]
	v_mfma_f32_32x32x16_bf16 v[80:95], v[162:165], v[176:179], v[80:95]
	v_exp_f32_e32 v112, v112
	v_exp_f32_e32 v113, v113
	v_exp_f32_e32 v114, v114
	v_exp_f32_e32 v115, v115
	v_mfma_f32_32x32x16_bf16 v[200:215], v[162:165], v[180:183], v[200:215]
	v_exp_f32_e32 v116, v116
	v_exp_f32_e32 v117, v117
	v_exp_f32_e32 v118, v118
	v_exp_f32_e32 v119, v119
	v_cvt_pk_bf16_f32 v162, v112, v113
	v_cvt_pk_bf16_f32 v163, v114, v115
	v_cvt_pk_bf16_f32 v164, v116, v117
	v_cvt_pk_bf16_f32 v165, v118, v119
	v_pk_add_f32 v[130:131], v[130:131], v[112:113]
	v_pk_add_f32 v[130:131], v[130:131], v[114:115]
	v_pk_add_f32 v[130:131], v[130:131], v[116:117]
	v_pk_add_f32 v[130:131], v[130:131], v[118:119]
	v_mfma_f32_32x32x16_bf16 v[80:95], v[162:165], v[184:187], v[80:95]
	v_exp_f32_e32 v120, v120
	v_exp_f32_e32 v121, v121
	v_exp_f32_e32 v122, v122
	v_exp_f32_e32 v123, v123
	v_mfma_f32_32x32x16_bf16 v[200:215], v[162:165], v[188:191], v[200:215]
	v_exp_f32_e32 v124, v124
	v_exp_f32_e32 v125, v125
	v_exp_f32_e32 v126, v126
	v_exp_f32_e32 v127, v127
	v_cvt_pk_bf16_f32 v162, v120, v121
	v_cvt_pk_bf16_f32 v163, v122, v123
	v_cvt_pk_bf16_f32 v164, v124, v125
	v_cvt_pk_bf16_f32 v165, v126, v127
	v_pk_add_f32 v[130:131], v[130:131], v[120:121]
	v_pk_add_f32 v[130:131], v[130:131], v[122:123]
	v_pk_add_f32 v[130:131], v[130:131], v[124:125]
	v_pk_add_f32 v[130:131], v[130:131], v[126:127]
	s_cmp_eq_u32 s33, 21
	s_cbranch_scc1 .Lat_w0F5
	s_waitcnt vmcnt(4)
	s_branch .Lat_wdF5

; __device__ __forceinline__ int crow(int r, int hi) { return (r & 3) + 8 * (r >> 2) + 4 * hi; }
; #define AT_LOAD(K0, K1, V0, V1, T) do { const size_t e_ = (size_t)(128 * (T) + sr) * 64 + sc; \
;         K0 = *(const bf16x8*)(kcp + e_); V0 = *(const bf16x8*)(vcp + e_); K1 = *(const bf16x8*)(kcp + e_ + 64 * 64); V1 = *(const bf16x8*)(vcp + e_ + 64 * 64); } while (0)
; #define AT_STORE(K0, K1, V0, V1, BUF) do { *(LAS bf16x8*)(lds + AT_K + (BUF) * AT_KB + kst0) = K0; *(LAS bf16x8*)(lds + AT_K + (BUF) * AT_KB + kst1) = K1; \
;         *(LAS bf16x8*)(lds + AT_V + (BUF) * AT_VB + vst0) = V0; *(LAS bf16x8*)(lds + AT_V + (BUF) * AT_VB + vst1) = V1; } while (0)
; template <int VAR>
; __device__ __forceinline__ void attn_unit(const Args& a, int l, int b, int h, int qrow0  , bool ctxu, const bf16* Z, bf16* Y, LAS unsigned char* lds) {
;     ...
;     for (int t = 0; t < NT; t += 2) {
;         __syncthreads();
;         if (t + 2 < NT) AT_LOAD(ka0, ka1, va0, va1, t + 2);
;         attn_tile(Kb0, vb0, q0, q1, negm, m, o0, o1, lacc, t == 0, wsf, r32, hi);
;         AT_STORE(kb0, kb1, vb0_, vb1_, 1);
;         __syncthreads();
;         if (t + 3 < NT) AT_LOAD(kb0, kb1, vb0_, vb1_, t + 3);
;         attn_tile(Kb0 + AT_KB, vb0 + AT_VB, q0, q1, negm, m, o0, o1, lacc, false, wsf, r32, hi);
;         if (t + 2 < NT) AT_STORE(ka0, ka1, va0, va1, 0);
;     }
;     ...
;     if (comp == 0) {
; #pragma unroll
;         for (int r = 0; r < 16; ++r) { const int qr = crow(r, hi); const float il = __builtin_amdgcn_rcpf(lacc[r]); o0[r] = o0[r] * il - stg[qr * 64 + r32]; o1[r] = o1[r] * il - stg[qr * 64 + 32 + r32]; }
;         asm volatile("s_waitcnt lgkmcnt(0)" ::: "memory");
; #pragma unroll
;         for (int r = 0; r < 16; ++r) { const int qr = crow(r, hi); stg[qr * 64 + r32] = o0[r]; stg[qr * 64 + 32 + r32] = o1[r]; }
;         asm volatile("s_waitcnt lgkmcnt(0)" ::: "memory");
;         const int ch = lane & 7;
;         float gsub[8];
; #pragma unroll
;         for (int i = 0; i < 8; ++i) gsub[i] = a.subln_g[l * 64 + ch * 8 + i] * omli;
.Lat_wdF5:
	s_waitcnt lgkmcnt(0)
	s_barrier
	s_cmp_eq_u32 s33, 21
	s_cbranch_scc1 .Lat_ndF5
.Lat_ndF5:
	ds_read_b128 v[48:51], v144 offset:0
	ds_read_b128 v[52:55], v145 offset:0
	ds_read_b128 v[56:59], v144 offset:4096
	ds_read_b128 v[60:63], v145 offset:4096
	v_mfma_f32_32x32x16_bf16 v[80:95], v[162:165], v[192:195], v[80:95]
	v_mfma_f32_32x32x16_bf16 v[200:215], v[162:165], v[196:199], v[200:215]
	s_add_u32 s33, s33, 1
	s_cmp_lt_u32 s33, 22
	s_cbranch_scc1 .Lat_floop
	v_add_f32_e32 v132, v128, v129
	v_mov_b32_e32 v133, v132
	s_nop 1
	v_permlane32_swap_b32_e32 v132, v133
	v_add_f32_e32 v135, v132, v133
	v_add_f32_e32 v132, v130, v131
	v_mov_b32_e32 v133, v132
	s_nop 1
	v_permlane32_swap_b32_e32 v132, v133
	v_add_f32_e32 v130, v132, v133
	s_nop 7
	s_nop 7
	v_add_f32_e32 v132, v135, v130
	v_mov_b32_e32 v133, 0
	v_add_f32_e64 v132, v132, |v0|
	v_add_f32_e64 v133, v133, |v1|
	v_add_f32_e64 v132, v132, |v2|
	v_add_f32_e64 v133, v133, |v3|
	v_add_f32_e64 v132, v132, |v4|
	v_add_f32_e64 v133, v133, |v5|
	v_add_f32_e64 v132, v132, |v6|
	v_add_f32_e64 v133, v133, |v7|
	v_add_f32_e64 v132, v132, |v8|
	v_add_f32_e64 v133, v133, |v9|
	v_add_f32_e64 v132, v132, |v10|
	v_add_f32_e64 v133, v133, |v11|
	v_add_f32_e64 v132, v132, |v12|
	v_add_f32_e64 v133, v133, |v13|
	v_add_f32_e64 v132, v132, |v14|
	v_add_f32_e64 v133, v133, |v15|
	v_add_f32_e64 v132, v132, |v16|
	v_add_f32_e64 v133, v133, |v17|
	v_add_f32_e64 v132, v132, |v18|
	v_add_f32_e64 v133, v133, |v19|
	v_add_f32_e64 v132, v132, |v20|
	v_add_f32_e64 v133, v133, |v21|
	v_add_f32_e64 v132, v132, |v22|
	v_add_f32_e64 v133, v133, |v23|
	v_add_f32_e64 v132, v132, |v24|
	v_add_f32_e64 v133, v133, |v25|
	v_add_f32_e64 v132, v132, |v26|
	v_add_f32_e64 v133, v133, |v27|
	v_add_f32_e64 v132, v132, |v28|
	v_add_f32_e64 v133, v133, |v29|
	v_add_f32_e64 v132, v132, |v30|
	v_add_f32_e64 v133, v133, |v31|
	v_add_f32_e64 v132, v132, |v80|
	v_add_f32_e64 v133, v133, |v81|
	v_add_f32_e64 v132, v132, |v82|
	v_add_f32_e64 v133, v133, |v83|
	v_add_f32_e64 v132, v132, |v84|
	v_add_f32_e64 v133, v133, |v85|
	v_add_f32_e64 v132, v132, |v86|
	v_add_f32_e64 v133, v133, |v87|
	v_add_f32_e64 v132, v132, |v88|
	v_add_f32_e64 v133, v133, |v89|
	v_add_f32_e64 v132, v132, |v90|
	v_add_f32_e64 v133, v133, |v91|
	v_add_f32_e64 v132, v132, |v92|
	v_add_f32_e64 v133, v133, |v93|
	v_add_f32_e64 v132, v132, |v94|
	v_add_f32_e64 v133, v133, |v95|
	v_add_f32_e64 v132, v132, |v200|
	v_add_f32_e64 v133, v133, |v201|
	v_add_f32_e64 v132, v132, |v202|
	v_add_f32_e64 v133, v133, |v203|
	v_add_f32_e64 v132, v132, |v204|
	v_add_f32_e64 v133, v133, |v205|
	v_add_f32_e64 v132, v132, |v206|
	v_add_f32_e64 v133, v133, |v207|
	v_add_f32_e64 v132, v132, |v208|
	v_add_f32_e64 v133, v133, |v209|
	v_add_f32_e64 v132, v132, |v210|
	v_add_f32_e64 v133, v133, |v211|
	v_add_f32_e64 v132, v132, |v212|
	v_add_f32_e64 v133, v133, |v213|
	v_add_f32_e64 v132, v132, |v214|
	v_add_f32_e64 v133, v133, |v215|
	v_add_f32_e32 v132, v132, v133
	v_mov_b32_e32 v133, 0x76800000
	v_cmp_nlt_f32_e32 vcc, v132, v133
	s_cmp_lg_u64 vcc, 0
	s_cselect_b32 s50, 1, 0
	v_mov_b32_e32 v134, 0x19880
	v_mov_b32_e32 v133, s50
	ds_or_b32 v134, v133
	s_waitcnt lgkmcnt(0)
	s_barrier
	ds_read_b32 v133, v134
	s_waitcnt lgkmcnt(0)
	v_readfirstlane_b32 s50, v133
	s_cmp_lg_u32 s50, 0
	s_cbranch_scc1 .Lat_safe_entry
	s_nop 7
	s_waitcnt lgkmcnt(0)
	ds_write_b32 v148, v135
	s_waitcnt lgkmcnt(0)
	ds_read_b128 v[32:35], v147 offset:0
	ds_read_b128 v[36:39], v147 offset:32
	ds_read_b128 v[40:43], v147 offset:64
	ds_read_b128 v[44:47], v147 offset:96
	s_waitcnt lgkmcnt(0)
	s_mov_b32 s93, 0
	s_waitcnt vmcnt(0)
	v_or_b32_e32 v132, s58, v228
	v_mov_b32_e32 v133, 0
	v_lshl_add_u64 v[132:133], v[132:133], 2, s[78:79]
	global_load_dwordx4 v[100:103], v[132:133], off offset:16
	global_load_dwordx4 v[96:99], v[132:133], off
	s_setprio 0
	s_branch .LBB0_459
